# P0: gate-weight staging loop unrolled (4 loads in flight, one wait) instead of 4 serial load/wait/ds_write trips
# speedup vs baseline: 1.0072x; 1.0072x over previous
; #define LAS __attribute__((address_space(3)))
; __device__ __forceinline__ void p0_prep(const Params& p, LAS unsigned char* lds) {
;     ...
;     for (int i = tid; i < 2048; i += 512) { const int k = i >> 1, hf = i & 1; *(LAS f32x4*)(WG + k * 8 + hf * 4) = *(const f32x4*)(p.w_in + (size_t)k * INW + 5120 + hf * 4); }
;     LAS float* strip = (LAS float*)(lds + 65536);
;     for (int tI = bid; tI < 928; tI += G) {
;         const float* src; bf16_t* dst; int ldn, Kdim, ns, kt, srccol;
;         int u = tI;
;         if (u < 768) { ns = u >> 4; kt = u & 15; src = p.w_in; ldn = INW; Kdim = 1024; dst = (bf16_t*)(ws + WS_WIN); srccol = ns * 256 + (ns >= 20 ? 8 : 0); }
;         else if (u < 832) { u -= 768; ns = u >> 4; kt = u & 15; src = p.w_pm; ldn = 1024; Kdim = 1024; dst = (bf16_t*)(ws + WS_WPM); srccol = ns * 256; }
;         else if (u < 864) { u -= 832; ns = u >> 3; kt = u & 7; src = p.w_pa; ldn = 1024; Kdim = 512; dst = (bf16_t*)(ws + WS_WPA); srccol = ns * 256; }
;         else { u -= 864; ns = u >> 4; kt = u & 15; src = p.w_out; ldn = 1024; Kdim = 1024; dst = (bf16_t*)(ws + WS_WOUT); srccol = ns * 256; }
;         float4 v[8];
; #pragma unroll
;         for (int i = 0; i < 8; ++i) { const int idx = tid + 512 * i; const int k = idx >> 6, n4 = idx & 63; const f32x4 t = __builtin_nontemporal_load((const f32x4*)(src + (size_t)(kt * 64 + k) * ldn + srccol + 4 * n4)); v[i] = make_float4(t[0], t[1], t[2], t[3]); }
; #pragma unroll
;         for (int i = 0; i < 8; ++i) { const int idx = tid + 512 * i; const int k = idx >> 6, n4 = idx & 63;
;             strip[k * 257 + 4 * n4 + 0] = v[i].x; strip[k * 257 + 4 * n4 + 1] = v[i].y; strip[k * 257 + 4 * n4 + 2] = v[i].z; strip[k * 257 + 4 * n4 + 3] = v[i].w; }
.LBB0_21:
	global_load_dwordx4 v[4:7], v[0:1], off
	v_lshl_add_u64 v[8:9], v[0:1], 0, s[2:3]
	global_load_dwordx4 v[12:15], v[8:9], off
	v_lshl_add_u64 v[8:9], v[8:9], 0, s[2:3]
	global_load_dwordx4 v[16:19], v[8:9], off
	v_lshl_add_u64 v[8:9], v[8:9], 0, s[2:3]
	global_load_dwordx4 v[20:23], v[8:9], off
	s_waitcnt vmcnt(0)
	ds_write_b128 v3, v[4:7]
	ds_write_b128 v3, v[12:15] offset:8192
	ds_write_b128 v3, v[16:19] offset:16384
	ds_write_b128 v3, v[20:23] offset:24576
	s_or_b64 exec, exec, s[0:1]
	s_lshl_b32 s13, s84, 4
	s_lshl_b32 s12, s82, 4
	s_cmpk_gt_i32 s84, 0x39f
	s_cbranch_scc1 .LBB0_37
	s_add_u32 s0, s88, 0x1b00000
	s_addc_u32 s1, s89, 0
	s_add_u32 s2, s88, 0x1800000
	s_addc_u32 s3, s89, 0
	v_lshlrev_b32_e32 v0, 2, v212
	s_add_u32 s4, s88, 0x1a00000
	v_and_b32_e32 v0, 0xfc, v0
	v_lshlrev_b32_e32 v1, 3, v212
	s_addc_u32 s5, s89, 0
	s_add_i32 s6, 0, 0x10000
	v_add_u32_e32 v9, 0x600, v212
	v_lshrrev_b32_e32 v6, 6, v212
	v_add_u32_e32 v14, 0x200, v212
	v_or_b32_e32 v15, 0x400, v212
	v_add_u32_e32 v11, 0xa00, v212
	v_add_u32_e32 v13, 0xe00, v212
	v_and_b32_e32 v2, 56, v1
	v_lshrrev_b32_e32 v4, 3, v212
	v_lshl_add_u32 v3, v0, 2, s6
	v_lshrrev_b32_e32 v5, 3, v9
	v_lshrrev_b32_e32 v7, 6, v14
	v_lshrrev_b32_e32 v8, 6, v15
	v_lshrrev_b32_e32 v9, 6, v9
	v_lshrrev_b32_e32 v11, 6, v11
	v_lshrrev_b32_e32 v13, 6, v13
	v_mul_u32_u24_e32 v16, 0x404, v6
	v_lshrrev_b32_e32 v14, 3, v14
	v_lshrrev_b32_e32 v15, 3, v15
	v_mov_b32_e32 v1, 0
	v_lshl_add_u32 v29, v5, 2, s6
	v_mul_u32_u24_e32 v30, 0x404, v2
	v_mul_u32_u24_e32 v17, 0x404, v7
	v_mul_u32_u24_e32 v18, 0x404, v8
	v_mul_u32_u24_e32 v19, 0x404, v9
	v_mul_u32_u24_e32 v22, 0x404, v11
	v_mul_u32_u24_e32 v25, 0x404, v13
	v_lshl_add_u32 v26, v4, 2, s6
	v_lshl_add_u32 v27, v14, 2, s6
	v_lshl_add_u32 v28, v15, 2, s6
	v_add_u32_e32 v16, v3, v16
	v_or_b32_e32 v10, 32, v6
	v_or_b32_e32 v12, 48, v6
	s_lshl_b32 s20, s84, 5
	s_lshl_b32 s21, s82, 5
	v_lshlrev_b32_e32 v0, 2, v0
	v_add_u32_e32 v17, v3, v17
	v_add_u32_e32 v18, v3, v18
	v_add_u32_e32 v19, v3, v19
	v_add_u32_e32 v20, 0x8080, v16
	v_add_u32_e32 v21, 0x8088, v16
	v_add_u32_e32 v22, v3, v22
	v_add_u32_e32 v23, 0xc0c0, v16
	v_add_u32_e32 v24, 0xc0c8, v16
	v_add_u32_e32 v25, v3, v25
	v_lshlrev_b32_e32 v2, 1, v2
	v_mov_b32_e32 v3, v1
	v_add_u32_e32 v26, v26, v30
	v_add_u32_e32 v27, v27, v30
	v_add_u32_e32 v28, v28, v30
	v_add_u32_e32 v29, v29, v30
	s_mov_b32 s22, s13
	s_mov_b32 s23, s84
	s_branch .LBB0_26
